# attention: static s_setprio 1 for waves 0-3 per unit instead of waves 4-7
# baseline (speedup 1.0000x reference)
; __device__ __forceinline__ int opaque_tid() { int t = threadIdx.x; asm volatile("" : "+v"(t)); return t; }
; template <bool MLA> ...
;     ...
;   const int tid = opaque_tid(), wid = __builtin_amdgcn_readfirstlane(tid >> 6), lane = tid & 63, r32 = lane & 31, hi = lane >> 5;
;   char* V_lds = lds + OFF_V; char* K_lds = lds + OFF_K; char* KR_lds = lds + OFF_KR;
;   float* ws = (float*)(lds + OFF_WS) + wid * 64; float* li_l = ws; float* al_l = ws + 32;
;   unsigned koff[2], voff[2], kroff = 0;
; #pragma unroll
;   for (int i = 0; i < 2; ++i) { const int p = 2 * wid + i;
; __global__ void __launch_bounds__(512) mega_fwd(Params p) {
;     ...
;             for (int u = bx; u < 3072; u += G) {
;                 const int mla = u / 1536, v = u % 1536, grp = v >> 8, w = v & 255, bh = grp * 8 + (w & 7), qb = w >> 3, b = bh >> 3, h = bh & 7;
;                 const size_t row0 = (size_t)b * SEQ, q0 = row0 + (size_t)qb * 256;
.LBB0_99:
	s_mul_hi_i32 s2, s12, 0x2aaaaaab
	s_lshr_b32 s3, s2, 31
	s_lshr_b32 s2, s2, 8
	s_add_i32 s2, s2, s3
	s_mulk_i32 s2, 0x600
	s_sub_i32 s13, s12, s2
	s_ashr_i32 s8, s13, 8
	s_ashr_i32 s9, s8, 31
	s_lshl_b32 s4, s13, 5
	s_lshl_b64 s[2:3], s[8:9], 13
	s_and_b32 s4, s4, 0x1f00
	s_or_b32 s2, s2, s4
	s_mulk_i32 s3, 0x1800
	s_mul_hi_u32 s5, s2, 0x1800
	s_and_b32 s16, s13, 7
	s_add_i32 s4, s12, 0x5ff
	s_add_i32 s5, s5, s3
	s_mulk_i32 s2, 0x1800
	s_add_u32 s17, s92, s2
	s_addc_u32 s18, s93, s5
	s_cmpk_gt_u32 s4, 0xbfe
	s_mov_b64 s[2:3], -1
	s_cbranch_scc0 .LBB0_115
	s_lshl_b32 s2, s16, 7
	s_lshl_b32 s3, s16, 8
	s_add_u32 s4, s17, s3
	s_addc_u32 s5, s18, 0
	s_add_u32 s2, s17, s2
	s_addc_u32 s3, s18, 0
	s_add_u32 s6, s2, 0x1000
	s_addc_u32 s7, s3, 0
	s_lshl_b64 s[2:3], s[8:9], 25
	s_add_u32 s10, s82, s2
	s_addc_u32 s11, s83, s3
	s_lshl_b32 s30, s16, 9
	s_add_u32 s24, s10, s30
	s_addc_u32 s25, s11, 0
	s_lshl_b64 s[10:11], s[8:9], 24
	v_readlane_b32 s14, v248, 43
	s_waitcnt vmcnt(0)
	v_mov_b32_e32 v64, v184
	v_readlane_b32 s15, v248, 44
	s_add_u32 s36, s14, s10
	s_addc_u32 s37, s15, s11
	v_readfirstlane_b32 s9, v64
	s_ashr_i32 s27, s9, 6
	s_cmp_ge_u32 s27, 4
	s_cbranch_scc1 .Lprio_skip_mla
	s_setprio 1

; __device__ __forceinline__ int opaque_tid() { int t = threadIdx.x; asm volatile("" : "+v"(t)); return t; }
; template <bool MLA> ...
;     ...
;   const int tid = opaque_tid(), wid = __builtin_amdgcn_readfirstlane(tid >> 6), lane = tid & 63, r32 = lane & 31, hi = lane >> 5;
;   char* V_lds = lds + OFF_V; char* K_lds = lds + OFF_K; char* KR_lds = lds + OFF_KR;
;   float* ws = (float*)(lds + OFF_WS) + wid * 64; float* li_l = ws; float* al_l = ws + 32;
;   unsigned koff[2], voff[2], kroff = 0;
; #pragma unroll
;   for (int i = 0; i < 2; ++i) { const int p = 2 * wid + i;
; __global__ void __launch_bounds__(512) mega_fwd(Params p) {
;     ...
;             for (int u = bx; u < 3072; u += G) {
;                 const int mla = u / 1536, v = u % 1536, grp = v >> 8, w = v & 255, bh = grp * 8 + (w & 7), qb = w >> 3, b = bh >> 3, h = bh & 7;
;                 const size_t row0 = (size_t)b * SEQ, q0 = row0 + (size_t)qb * 256;
;                 if (!mla) {
;                     att::attn_unit<false>(QQ + q0 * LDQQ + h * 128, nullptr, QQ + row0 * LDQQ + 2560 + (h >> 2) * 128, nullptr, QQ + row0 * LDQQ + 2816 + (h >> 2) * 128,
.LBB0_124:
	s_lshl_b32 s2, s16, 8
	s_add_u32 s4, s17, s2
	s_addc_u32 s5, s18, 0
	s_mul_i32 s2, s8, 0x3000000
	s_mul_hi_i32 s3, s8, 0x3000000
	s_add_u32 s6, s92, s2
	s_addc_u32 s7, s93, s3
	s_lshl_b32 s8, s16, 6
	s_and_b32 s8, s8, 0x100
	s_add_u32 s6, s6, s8
	s_addc_u32 s7, s7, 0
	v_mov_b32_e32 v74, v184
	s_add_u32 s16, s6, 0x1400
	s_addc_u32 s17, s7, 0
	v_readfirstlane_b32 s9, v74
	s_ashr_i32 s8, s9, 6
	s_cmp_ge_u32 s8, 4
	s_cbranch_scc1 .Lprio_skip_gqa
	s_setprio 1
